# phase H: next tile's row scales prepared in the epilogue; no vmcnt(0) store drain at the tile end nor before the first LDS-DMA loads of later tiles
# speedup vs baseline: 1.0048x; 1.0048x over previous
; DI uint2 pk4(float a, float b, float c, float d) { uint2 o; o.x = pk2(a, b); o.y = pk2(c, d); return o; }
; DI void phaseH(int wv0, PP p, unsigned char* smem) {
;     ...
;   for (int id = blockIdx.x; id < 128 * 16; id += gridDim.x) {
;     int pm, pn;
;     tile_map_n16(id, pm, pn);
;     const int brow = pm * 256, bcol = pn * 256;
;     const int tid = my_tid(wv0);
;     if (tid < 256) {
;       const float4* s = (const float4*)(SS1 + (size_t)(brow + tid) * 16);
;       const float4 a = s[0], b = s[1], c = s[2], d = s[3];
;       const float t = a.x + a.y + a.z + a.w + b.x + b.y + b.z + b.w + c.x + c.y + c.z + c.w + d.x + d.y + d.z + d.w;
;       sR[tid] = rsqrtf(t * (1.f / 1024.f) + 1e-6f);
;     }
;     f32x4 acc[2][2][4][2];
;     gemm256(wv0, acc, X1B + (size_t)brow * 1024, 1024, (const u16*)(p->ws + OFF_WUPT) + (size_t)bcol * 1024, 1024, 1024, smem);
;     epi256(wv0, acc, brow, bcol, [&](int ai, int bj, int m, int n, int row, int col0, f32x4& v) {
;       const float ri = sR[row - brow];
;       const float a0 = fmaxf(v[0] * ri, 0.f), a1 = fmaxf(v[1] * ri, 0.f), a2 = fmaxf(v[2] * ri, 0.f), a3 = fmaxf(v[3] * ri, 0.f);
;       *(uint2*)(ACT + (size_t)row * 4096 + col0) = pk4(a0 * a0, a1 * a1, a2 * a2, a3 * a3);
;     });
.LBB0_1131:
	s_cmpk_gt_i32 s94, 0x7ff
	s_cbranch_scc1 .LBB0_1142
	s_load_dwordx2 s[2:3], s[4:5], 0xc8
	v_mbcnt_lo_u32_b32 v0, -1, 0
	v_mbcnt_hi_u32_b32 v0, -1, v0
	s_mov_b32 s5, 0
	s_movk_i32 s55, 0x100
	s_waitcnt lgkmcnt(0)
	s_add_u32 s0, s2, 0x133d4100
	s_addc_u32 s1, s3, 0
	s_add_u32 s8, s2, 0x1fd4100
	s_addc_u32 s9, s3, 0
	s_add_u32 s10, s2, 0x33d4100
	s_addc_u32 s11, s3, 0
	s_and_b32 s4, s82, 0xffffffc0
	s_add_u32 s33, s2, 0xf40000
	v_add_u32_e32 v142, s4, v0
	s_addc_u32 s50, s3, 0
	s_lshr_b32 s4, s82, 8
	s_cmp_eq_u32 s4, 1
	s_cselect_b64 s[12:13], -1, 0
	s_lshl_b32 s51, s4, 6
	s_lshl_b32 s14, s89, 12
	s_or_b32 s52, s51, 16
	s_or_b32 s53, s51, 32
	s_or_b32 s54, s51, 48
	s_and_b32 s18, s14, 0x3000
	s_lshl_b32 s4, s4, 13
	s_lshl_b32 s19, s52, 7
	s_lshl_b32 s20, s53, 7
	s_lshl_b32 s21, s54, 7
	s_cmpk_lt_u32 s82, 0x100
	s_cselect_b64 s[14:15], -1, 0
	s_lshl_b32 s16, s89, 4
	s_and_b32 s56, s16, 0x3fffffc0
	s_lshl_b32 s16, s89, 5
	s_and_b32 s57, s16, 0x60
	s_add_u32 s16, s90, 0xd8
	s_addc_u32 s17, s91, 0
	s_add_i32 s65, s18, 32
	s_add_i32 s58, s65, 0x10000
	s_add_i32 s59, s4, 32
	s_add_i32 s60, s19, 32
	s_add_i32 s61, s20, 32
	s_add_i32 s62, s21, 32
	s_add_i32 s63, s65, 0x14000
	s_add_i32 s64, s65, 0x18000
	s_add_i32 s65, s65, 0x1c000
	v_mov_b32_e32 v143, 0x358637bd
	s_mov_b32 s66, 0x800000
	s_mov_b64 s[18:19], 0x40000
	s_mov_b64 s[20:21], 0x80
	s_mov_b64 s[22:23], 0x40080
	s_mov_b64 s[24:25], 0x13414180
	s_mov_b64 s[26:27], 0xf40100
	s_mov_b64 s[28:29], 0x133d4200
	s_mov_b64 s[30:31], 0xf80100
	s_mov_b64 s[34:35], 0x13414200
	s_mov_b64 s[36:37], 0xf40180
	s_mov_b64 s[38:39], 0x133d4280
	s_mov_b64 s[40:41], 0xf80180
	s_mov_b64 s[42:43], 0x100
	s_mov_b64 s[44:45], 0x40780
	v_mov_b32_e32 v129, 0
	v_mov_b32_e32 v144, 1
	s_mov_b32 s67, s94
	s_mov_b32 s80, 0
	s_branch .LBB0_1134
.Lmy_hn_exit:
	s_waitcnt vmcnt(0)
	s_branch .LBB0_1142
.LBB0_1133:
	s_load_dword s88, s[16:17], 0x0
	s_waitcnt lgkmcnt(0)
	s_add_i32 s88, s88, s67
	s_cmpk_lt_i32 s88, 0x800
	s_cbranch_scc0 .Lmy_hw_skip
	s_ashr_i32 s83, s88, 4
	s_and_b32 s83, s83, -16
	s_lshl_b32 s84, s88, 1
	s_and_b32 s84, s84, 12
	s_or_b32 s83, s83, s84
	s_bfe_u32 s84, s88, 0x20006
	s_or_b32 s83, s83, s84
	s_lshl_b32 s84, s83, 8
	s_mov_b32 s80, 1
	v_and_b32_e32 v184, 0xff, v142
	v_add_u32_e32 v184, s84, v184
	v_mov_b32_e32 v185, 0
	v_lshlrev_b64 v[184:185], 6, v[184:185]
	v_lshl_add_u64 v[184:185], s[8:9], 0, v[184:185]
	global_load_dwordx4 v[168:171], v[184:185], off
	global_load_dwordx4 v[172:175], v[184:185], off offset:16
	global_load_dwordx4 v[176:179], v[184:185], off offset:32
	global_load_dwordx4 v[180:183], v[184:185], off offset:48
	s_mov_b32 s85, 0
	s_lshl_b64 s[84:85], s[84:85], 11
	s_add_u32 s84, s0, s84
	s_addc_u32 s85, s1, s85
	s_lshl_b32 s86, s88, 3
	s_and_b32 s86, s86, 8
	s_bfe_u32 s87, s88, 0x30003
	s_or_b32 s86, s86, s87
	s_lshl_b32 s86, s86, 19
	s_add_u32 s86, s33, s86
	s_addc_u32 s87, s50, 0
	v_and_b32_e32 v236, 0xff, v142
	v_lshlrev_b32_e32 v236, 11, v236
	v_mov_b32_e32 v238, s84
	v_mov_b32_e32 v239, s85
	v_mov_b32_e32 v240, s86
	v_mov_b32_e32 v241, s87
	v_cmp_gt_u32_e32 vcc, 0x100, v142
	s_nop 1
	v_cndmask_b32_e32 v238, v240, v238, vcc
	v_cndmask_b32_e32 v239, v241, v239, vcc
	v_add_co_u32_e32 v238, vcc, v238, v236
	v_addc_co_u32_e32 v239, vcc, 0, v239, vcc
	global_load_dword v237, v[238:239], off
.Lmy_hw_skip:
	v_and_b32_e32 v130, 15, v142
	v_bfe_u32 v131, v142, 4, 2
	v_add_u32_e32 v132, s51, v130
	v_lshlrev_b32_e32 v133, 2, v132
	v_add_u32_e32 v133, 0x21400, v133
	ds_read_b32 v200, v133 offset:0
	ds_read_b32 v202, v133 offset:64
	ds_read_b32 v204, v133 offset:128
	ds_read_b32 v206, v133 offset:192
	ds_read_b32 v208, v133 offset:512
	ds_read_b32 v210, v133 offset:576
	ds_read_b32 v212, v133 offset:640
	ds_read_b32 v214, v133 offset:704
	v_mul_u32_u24_e32 v134, 528, v132
	v_lshlrev_b32_e32 v135, 3, v131
	s_lshl_b32 s78, s57, 1
	v_add3_u32 v134, v134, v135, s78
	v_add_u32_e32 v134, 32, v134
	v_add_u32_e32 v136, 67584, v134
	s_waitcnt lgkmcnt(0)
	v_mul_f32_e32 v124, v124, v200
	v_mul_f32_e32 v125, v125, v200
	v_mul_f32_e32 v126, v126, v200
	v_mul_f32_e32 v127, v127, v200
	v_max_f32_e32 v124, 0, v124
	v_max_f32_e32 v125, 0, v125
	v_max_f32_e32 v126, 0, v126
	v_max_f32_e32 v127, 0, v127
	v_pk_mul_f32 v[124:125], v[124:125], v[124:125]
	v_pk_mul_f32 v[126:127], v[126:127], v[126:127]
	v_cvt_pk_bf16_f32 v124, v124, v125
	v_cvt_pk_bf16_f32 v125, v126, v127
	ds_write_b64 v134, v[124:125] offset:0
	v_mul_f32_e32 v120, v120, v200
	v_mul_f32_e32 v121, v121, v200
	v_mul_f32_e32 v122, v122, v200
	v_mul_f32_e32 v123, v123, v200
	v_max_f32_e32 v120, 0, v120
	v_max_f32_e32 v121, 0, v121
	v_max_f32_e32 v122, 0, v122
	v_max_f32_e32 v123, 0, v123
	v_pk_mul_f32 v[120:121], v[120:121], v[120:121]
	v_pk_mul_f32 v[122:123], v[122:123], v[122:123]
	v_cvt_pk_bf16_f32 v120, v120, v121
	v_cvt_pk_bf16_f32 v121, v122, v123
	ds_write_b64 v134, v[120:121] offset:32
	v_mul_f32_e32 v116, v116, v202
	v_mul_f32_e32 v117, v117, v202
	v_mul_f32_e32 v118, v118, v202
	v_mul_f32_e32 v119, v119, v202
	v_max_f32_e32 v116, 0, v116
	v_max_f32_e32 v117, 0, v117
	v_max_f32_e32 v118, 0, v118
	v_max_f32_e32 v119, 0, v119
	v_pk_mul_f32 v[116:117], v[116:117], v[116:117]
	v_pk_mul_f32 v[118:119], v[118:119], v[118:119]
	v_cvt_pk_bf16_f32 v116, v116, v117
	v_cvt_pk_bf16_f32 v117, v118, v119
	ds_write_b64 v134, v[116:117] offset:8448
	v_mul_f32_e32 v112, v112, v202
	v_mul_f32_e32 v113, v113, v202
	v_mul_f32_e32 v114, v114, v202
	v_mul_f32_e32 v115, v115, v202
	v_max_f32_e32 v112, 0, v112
	v_max_f32_e32 v113, 0, v113
	v_max_f32_e32 v114, 0, v114
	v_max_f32_e32 v115, 0, v115
	v_pk_mul_f32 v[112:113], v[112:113], v[112:113]
; DI uint2 pk4(float a, float b, float c, float d) { uint2 o; o.x = pk2(a, b); o.y = pk2(c, d); return o; }
; DI void phaseH(int wv0, PP p, unsigned char* smem) {
;     ...
;     epi256(wv0, acc, brow, bcol, [&](int ai, int bj, int m, int n, int row, int col0, f32x4& v) {
;       const float ri = sR[row - brow];
;       const float a0 = fmaxf(v[0] * ri, 0.f), a1 = fmaxf(v[1] * ri, 0.f), a2 = fmaxf(v[2] * ri, 0.f), a3 = fmaxf(v[3] * ri, 0.f);
;       *(uint2*)(ACT + (size_t)row * 4096 + col0) = pk4(a0 * a0, a1 * a1, a2 * a2, a3 * a3);
;     });
	v_pk_mul_f32 v[114:115], v[114:115], v[114:115]
	v_cvt_pk_bf16_f32 v112, v112, v113
	v_cvt_pk_bf16_f32 v113, v114, v115
	ds_write_b64 v134, v[112:113] offset:8480
	v_mul_f32_e32 v108, v108, v204
	v_mul_f32_e32 v109, v109, v204
	v_mul_f32_e32 v110, v110, v204
	v_mul_f32_e32 v111, v111, v204
	v_max_f32_e32 v108, 0, v108
	v_max_f32_e32 v109, 0, v109
	v_max_f32_e32 v110, 0, v110
	v_max_f32_e32 v111, 0, v111
	v_pk_mul_f32 v[108:109], v[108:109], v[108:109]
	v_pk_mul_f32 v[110:111], v[110:111], v[110:111]
	v_cvt_pk_bf16_f32 v108, v108, v109
	v_cvt_pk_bf16_f32 v109, v110, v111
	ds_write_b64 v134, v[108:109] offset:16896
	v_mul_f32_e32 v104, v104, v204
	v_mul_f32_e32 v105, v105, v204
	v_mul_f32_e32 v106, v106, v204
	v_mul_f32_e32 v107, v107, v204
	v_max_f32_e32 v104, 0, v104
	v_max_f32_e32 v105, 0, v105
	v_max_f32_e32 v106, 0, v106
	v_max_f32_e32 v107, 0, v107
	v_pk_mul_f32 v[104:105], v[104:105], v[104:105]
	v_pk_mul_f32 v[106:107], v[106:107], v[106:107]
	v_cvt_pk_bf16_f32 v104, v104, v105
	v_cvt_pk_bf16_f32 v105, v106, v107
	ds_write_b64 v134, v[104:105] offset:16928
	v_mul_f32_e32 v100, v100, v206
	v_mul_f32_e32 v101, v101, v206
	v_mul_f32_e32 v102, v102, v206
	v_mul_f32_e32 v103, v103, v206
	v_max_f32_e32 v100, 0, v100
	v_max_f32_e32 v101, 0, v101
	v_max_f32_e32 v102, 0, v102
	v_max_f32_e32 v103, 0, v103
	v_pk_mul_f32 v[100:101], v[100:101], v[100:101]
	v_pk_mul_f32 v[102:103], v[102:103], v[102:103]
	v_cvt_pk_bf16_f32 v100, v100, v101
	v_cvt_pk_bf16_f32 v101, v102, v103
	ds_write_b64 v134, v[100:101] offset:25344
	v_mul_f32_e32 v96, v96, v206
	v_mul_f32_e32 v97, v97, v206
	v_mul_f32_e32 v98, v98, v206
	v_mul_f32_e32 v99, v99, v206
	v_max_f32_e32 v96, 0, v96
	v_max_f32_e32 v97, 0, v97
	v_max_f32_e32 v98, 0, v98
	v_max_f32_e32 v99, 0, v99
	v_pk_mul_f32 v[96:97], v[96:97], v[96:97]
	v_pk_mul_f32 v[98:99], v[98:99], v[98:99]
	v_cvt_pk_bf16_f32 v96, v96, v97
	v_cvt_pk_bf16_f32 v97, v98, v99
	ds_write_b64 v134, v[96:97] offset:25376
	v_mul_f32_e32 v92, v92, v200
	v_mul_f32_e32 v93, v93, v200
	v_mul_f32_e32 v94, v94, v200
	v_mul_f32_e32 v95, v95, v200
	v_max_f32_e32 v92, 0, v92
	v_max_f32_e32 v93, 0, v93
	v_max_f32_e32 v94, 0, v94
	v_max_f32_e32 v95, 0, v95
	v_pk_mul_f32 v[92:93], v[92:93], v[92:93]
	v_pk_mul_f32 v[94:95], v[94:95], v[94:95]
	v_cvt_pk_bf16_f32 v92, v92, v93
	v_cvt_pk_bf16_f32 v93, v94, v95
	ds_write_b64 v134, v[92:93] offset:256
	v_mul_f32_e32 v88, v88, v200
	v_mul_f32_e32 v89, v89, v200
	v_mul_f32_e32 v90, v90, v200
	v_mul_f32_e32 v91, v91, v200
	v_max_f32_e32 v88, 0, v88
	v_max_f32_e32 v89, 0, v89
	v_max_f32_e32 v90, 0, v90
	v_max_f32_e32 v91, 0, v91
	v_pk_mul_f32 v[88:89], v[88:89], v[88:89]
	v_pk_mul_f32 v[90:91], v[90:91], v[90:91]
	v_cvt_pk_bf16_f32 v88, v88, v89
	v_cvt_pk_bf16_f32 v89, v90, v91
	ds_write_b64 v134, v[88:89] offset:288
	v_mul_f32_e32 v84, v84, v202
	v_mul_f32_e32 v85, v85, v202
	v_mul_f32_e32 v86, v86, v202
	v_mul_f32_e32 v87, v87, v202
	v_max_f32_e32 v84, 0, v84
	v_max_f32_e32 v85, 0, v85
	v_max_f32_e32 v86, 0, v86
	v_max_f32_e32 v87, 0, v87
	v_pk_mul_f32 v[84:85], v[84:85], v[84:85]
	v_pk_mul_f32 v[86:87], v[86:87], v[86:87]
	v_cvt_pk_bf16_f32 v84, v84, v85
	v_cvt_pk_bf16_f32 v85, v86, v87
	ds_write_b64 v134, v[84:85] offset:8704
	v_mul_f32_e32 v80, v80, v202
	v_mul_f32_e32 v81, v81, v202
	v_mul_f32_e32 v82, v82, v202
	v_mul_f32_e32 v83, v83, v202
	v_max_f32_e32 v80, 0, v80
	v_max_f32_e32 v81, 0, v81
	v_max_f32_e32 v82, 0, v82
	v_max_f32_e32 v83, 0, v83
	v_pk_mul_f32 v[80:81], v[80:81], v[80:81]
	v_pk_mul_f32 v[82:83], v[82:83], v[82:83]
	v_cvt_pk_bf16_f32 v80, v80, v81
	v_cvt_pk_bf16_f32 v81, v82, v83
	ds_write_b64 v134, v[80:81] offset:8736
	v_mul_f32_e32 v76, v76, v204
	v_mul_f32_e32 v77, v77, v204
	v_mul_f32_e32 v78, v78, v204
	v_mul_f32_e32 v79, v79, v204
	v_max_f32_e32 v76, 0, v76
	v_max_f32_e32 v77, 0, v77
	v_max_f32_e32 v78, 0, v78
	v_max_f32_e32 v79, 0, v79
	v_pk_mul_f32 v[76:77], v[76:77], v[76:77]
	v_pk_mul_f32 v[78:79], v[78:79], v[78:79]
	v_cvt_pk_bf16_f32 v76, v76, v77
	v_cvt_pk_bf16_f32 v77, v78, v79
	ds_write_b64 v134, v[76:77] offset:17152
	v_mul_f32_e32 v72, v72, v204
	v_mul_f32_e32 v73, v73, v204
	v_mul_f32_e32 v74, v74, v204
	v_mul_f32_e32 v75, v75, v204
	v_max_f32_e32 v72, 0, v72
	v_max_f32_e32 v73, 0, v73
	v_max_f32_e32 v74, 0, v74
	v_max_f32_e32 v75, 0, v75
	v_pk_mul_f32 v[72:73], v[72:73], v[72:73]
	v_pk_mul_f32 v[74:75], v[74:75], v[74:75]
	v_cvt_pk_bf16_f32 v72, v72, v73
	v_cvt_pk_bf16_f32 v73, v74, v75
	ds_write_b64 v134, v[72:73] offset:17184
	v_mul_f32_e32 v68, v68, v206
	v_mul_f32_e32 v69, v69, v206
	v_mul_f32_e32 v70, v70, v206
	v_mul_f32_e32 v71, v71, v206
	v_max_f32_e32 v68, 0, v68
	v_max_f32_e32 v69, 0, v69
	v_max_f32_e32 v70, 0, v70
	v_max_f32_e32 v71, 0, v71
	v_pk_mul_f32 v[68:69], v[68:69], v[68:69]
	v_pk_mul_f32 v[70:71], v[70:71], v[70:71]
	v_cvt_pk_bf16_f32 v68, v68, v69
	v_cvt_pk_bf16_f32 v69, v70, v71
	ds_write_b64 v134, v[68:69] offset:25600
	v_mul_f32_e32 v64, v64, v206
	v_mul_f32_e32 v65, v65, v206
	v_mul_f32_e32 v66, v66, v206
	v_mul_f32_e32 v67, v67, v206
	v_max_f32_e32 v64, 0, v64
	v_max_f32_e32 v65, 0, v65
	v_max_f32_e32 v66, 0, v66
	v_max_f32_e32 v67, 0, v67
	v_pk_mul_f32 v[64:65], v[64:65], v[64:65]
	v_pk_mul_f32 v[66:67], v[66:67], v[66:67]
	v_cvt_pk_bf16_f32 v64, v64, v65
	v_cvt_pk_bf16_f32 v65, v66, v67
	ds_write_b64 v134, v[64:65] offset:25632
	v_mul_f32_e32 v60, v60, v208
	v_mul_f32_e32 v61, v61, v208
	v_mul_f32_e32 v62, v62, v208
	v_mul_f32_e32 v63, v63, v208
	v_max_f32_e32 v60, 0, v60
	v_max_f32_e32 v61, 0, v61
	v_max_f32_e32 v62, 0, v62
	v_max_f32_e32 v63, 0, v63
	v_pk_mul_f32 v[60:61], v[60:61], v[60:61]
	v_pk_mul_f32 v[62:63], v[62:63], v[62:63]
; DI uint2 pk4(float a, float b, float c, float d) { uint2 o; o.x = pk2(a, b); o.y = pk2(c, d); return o; }
; DI void phaseH(int wv0, PP p, unsigned char* smem) {
;     ...
;     epi256(wv0, acc, brow, bcol, [&](int ai, int bj, int m, int n, int row, int col0, f32x4& v) {
;       const float ri = sR[row - brow];
;       const float a0 = fmaxf(v[0] * ri, 0.f), a1 = fmaxf(v[1] * ri, 0.f), a2 = fmaxf(v[2] * ri, 0.f), a3 = fmaxf(v[3] * ri, 0.f);
;       *(uint2*)(ACT + (size_t)row * 4096 + col0) = pk4(a0 * a0, a1 * a1, a2 * a2, a3 * a3);
;     });
	v_cvt_pk_bf16_f32 v60, v60, v61
	v_cvt_pk_bf16_f32 v61, v62, v63
	ds_write_b64 v136, v[60:61] offset:0
	v_mul_f32_e32 v56, v56, v208
	v_mul_f32_e32 v57, v57, v208
	v_mul_f32_e32 v58, v58, v208
	v_mul_f32_e32 v59, v59, v208
	v_max_f32_e32 v56, 0, v56
	v_max_f32_e32 v57, 0, v57
	v_max_f32_e32 v58, 0, v58
	v_max_f32_e32 v59, 0, v59
	v_pk_mul_f32 v[56:57], v[56:57], v[56:57]
	v_pk_mul_f32 v[58:59], v[58:59], v[58:59]
	v_cvt_pk_bf16_f32 v56, v56, v57
	v_cvt_pk_bf16_f32 v57, v58, v59
	ds_write_b64 v136, v[56:57] offset:32
	v_mul_f32_e32 v52, v52, v210
	v_mul_f32_e32 v53, v53, v210
	v_mul_f32_e32 v54, v54, v210
	v_mul_f32_e32 v55, v55, v210
	v_max_f32_e32 v52, 0, v52
	v_max_f32_e32 v53, 0, v53
	v_max_f32_e32 v54, 0, v54
	v_max_f32_e32 v55, 0, v55
	v_pk_mul_f32 v[52:53], v[52:53], v[52:53]
	v_pk_mul_f32 v[54:55], v[54:55], v[54:55]
	v_cvt_pk_bf16_f32 v52, v52, v53
	v_cvt_pk_bf16_f32 v53, v54, v55
	ds_write_b64 v136, v[52:53] offset:8448
	v_mul_f32_e32 v48, v48, v210
	v_mul_f32_e32 v49, v49, v210
	v_mul_f32_e32 v50, v50, v210
	v_mul_f32_e32 v51, v51, v210
	v_max_f32_e32 v48, 0, v48
	v_max_f32_e32 v49, 0, v49
	v_max_f32_e32 v50, 0, v50
	v_max_f32_e32 v51, 0, v51
	v_pk_mul_f32 v[48:49], v[48:49], v[48:49]
	v_pk_mul_f32 v[50:51], v[50:51], v[50:51]
	v_cvt_pk_bf16_f32 v48, v48, v49
	v_cvt_pk_bf16_f32 v49, v50, v51
	ds_write_b64 v136, v[48:49] offset:8480
	v_mul_f32_e32 v44, v44, v212
	v_mul_f32_e32 v45, v45, v212
	v_mul_f32_e32 v46, v46, v212
	v_mul_f32_e32 v47, v47, v212
	v_max_f32_e32 v44, 0, v44
	v_max_f32_e32 v45, 0, v45
	v_max_f32_e32 v46, 0, v46
	v_max_f32_e32 v47, 0, v47
	v_pk_mul_f32 v[44:45], v[44:45], v[44:45]
	v_pk_mul_f32 v[46:47], v[46:47], v[46:47]
	v_cvt_pk_bf16_f32 v44, v44, v45
	v_cvt_pk_bf16_f32 v45, v46, v47
	ds_write_b64 v136, v[44:45] offset:16896
	v_mul_f32_e32 v40, v40, v212
	v_mul_f32_e32 v41, v41, v212
	v_mul_f32_e32 v42, v42, v212
	v_mul_f32_e32 v43, v43, v212
	v_max_f32_e32 v40, 0, v40
	v_max_f32_e32 v41, 0, v41
	v_max_f32_e32 v42, 0, v42
	v_max_f32_e32 v43, 0, v43
	v_pk_mul_f32 v[40:41], v[40:41], v[40:41]
	v_pk_mul_f32 v[42:43], v[42:43], v[42:43]
	v_cvt_pk_bf16_f32 v40, v40, v41
	v_cvt_pk_bf16_f32 v41, v42, v43
	ds_write_b64 v136, v[40:41] offset:16928
	v_mul_f32_e32 v36, v36, v214
	v_mul_f32_e32 v37, v37, v214
	v_mul_f32_e32 v38, v38, v214
	v_mul_f32_e32 v39, v39, v214
	v_max_f32_e32 v36, 0, v36
	v_max_f32_e32 v37, 0, v37
	v_max_f32_e32 v38, 0, v38
	v_max_f32_e32 v39, 0, v39
	v_pk_mul_f32 v[36:37], v[36:37], v[36:37]
	v_pk_mul_f32 v[38:39], v[38:39], v[38:39]
	v_cvt_pk_bf16_f32 v36, v36, v37
	v_cvt_pk_bf16_f32 v37, v38, v39
	ds_write_b64 v136, v[36:37] offset:25344
	v_mul_f32_e32 v32, v32, v214
	v_mul_f32_e32 v33, v33, v214
	v_mul_f32_e32 v34, v34, v214
	v_mul_f32_e32 v35, v35, v214
	v_max_f32_e32 v32, 0, v32
	v_max_f32_e32 v33, 0, v33
	v_max_f32_e32 v34, 0, v34
	v_max_f32_e32 v35, 0, v35
	v_pk_mul_f32 v[32:33], v[32:33], v[32:33]
	v_pk_mul_f32 v[34:35], v[34:35], v[34:35]
	v_cvt_pk_bf16_f32 v32, v32, v33
	v_cvt_pk_bf16_f32 v33, v34, v35
	ds_write_b64 v136, v[32:33] offset:25376
	v_mul_f32_e32 v28, v28, v208
	v_mul_f32_e32 v29, v29, v208
	v_mul_f32_e32 v30, v30, v208
	v_mul_f32_e32 v31, v31, v208
	v_max_f32_e32 v28, 0, v28
	v_max_f32_e32 v29, 0, v29
	v_max_f32_e32 v30, 0, v30
	v_max_f32_e32 v31, 0, v31
	v_pk_mul_f32 v[28:29], v[28:29], v[28:29]
	v_pk_mul_f32 v[30:31], v[30:31], v[30:31]
	v_cvt_pk_bf16_f32 v28, v28, v29
	v_cvt_pk_bf16_f32 v29, v30, v31
	ds_write_b64 v136, v[28:29] offset:256
	v_mul_f32_e32 v24, v24, v208
	v_mul_f32_e32 v25, v25, v208
	v_mul_f32_e32 v26, v26, v208
	v_mul_f32_e32 v27, v27, v208
	v_max_f32_e32 v24, 0, v24
	v_max_f32_e32 v25, 0, v25
	v_max_f32_e32 v26, 0, v26
	v_max_f32_e32 v27, 0, v27
	v_pk_mul_f32 v[24:25], v[24:25], v[24:25]
	v_pk_mul_f32 v[26:27], v[26:27], v[26:27]
	v_cvt_pk_bf16_f32 v24, v24, v25
	v_cvt_pk_bf16_f32 v25, v26, v27
	ds_write_b64 v136, v[24:25] offset:288
	v_mul_f32_e32 v20, v20, v210
	v_mul_f32_e32 v21, v21, v210
	v_mul_f32_e32 v22, v22, v210
	v_mul_f32_e32 v23, v23, v210
	v_max_f32_e32 v20, 0, v20
	v_max_f32_e32 v21, 0, v21
	v_max_f32_e32 v22, 0, v22
	v_max_f32_e32 v23, 0, v23
	v_pk_mul_f32 v[20:21], v[20:21], v[20:21]
	v_pk_mul_f32 v[22:23], v[22:23], v[22:23]
	v_cvt_pk_bf16_f32 v20, v20, v21
	v_cvt_pk_bf16_f32 v21, v22, v23
	ds_write_b64 v136, v[20:21] offset:8704
	v_mul_f32_e32 v16, v16, v210
	v_mul_f32_e32 v17, v17, v210
	v_mul_f32_e32 v18, v18, v210
	v_mul_f32_e32 v19, v19, v210
	v_max_f32_e32 v16, 0, v16
	v_max_f32_e32 v17, 0, v17
	v_max_f32_e32 v18, 0, v18
	v_max_f32_e32 v19, 0, v19
	v_pk_mul_f32 v[16:17], v[16:17], v[16:17]
	v_pk_mul_f32 v[18:19], v[18:19], v[18:19]
	v_cvt_pk_bf16_f32 v16, v16, v17
	v_cvt_pk_bf16_f32 v17, v18, v19
	ds_write_b64 v136, v[16:17] offset:8736
	v_mul_f32_e32 v12, v12, v212
	v_mul_f32_e32 v13, v13, v212
	v_mul_f32_e32 v14, v14, v212
	v_mul_f32_e32 v15, v15, v212
	v_max_f32_e32 v12, 0, v12
	v_max_f32_e32 v13, 0, v13
	v_max_f32_e32 v14, 0, v14
	v_max_f32_e32 v15, 0, v15
	v_pk_mul_f32 v[12:13], v[12:13], v[12:13]
	v_pk_mul_f32 v[14:15], v[14:15], v[14:15]
	v_cvt_pk_bf16_f32 v12, v12, v13
	v_cvt_pk_bf16_f32 v13, v14, v15
	ds_write_b64 v136, v[12:13] offset:17152
	v_mul_f32_e32 v8, v8, v212
	v_mul_f32_e32 v9, v9, v212
	v_mul_f32_e32 v10, v10, v212
	v_mul_f32_e32 v11, v11, v212
	v_max_f32_e32 v8, 0, v8
	v_max_f32_e32 v9, 0, v9
	v_max_f32_e32 v10, 0, v10
	v_max_f32_e32 v11, 0, v11
	v_pk_mul_f32 v[8:9], v[8:9], v[8:9]
	v_pk_mul_f32 v[10:11], v[10:11], v[10:11]
	v_cvt_pk_bf16_f32 v8, v8, v9
	v_cvt_pk_bf16_f32 v9, v10, v11
	ds_write_b64 v136, v[8:9] offset:17184
	v_mul_f32_e32 v4, v4, v214
	v_mul_f32_e32 v5, v5, v214
	v_mul_f32_e32 v6, v6, v214
	v_mul_f32_e32 v7, v7, v214
	v_max_f32_e32 v4, 0, v4
	v_max_f32_e32 v5, 0, v5
	v_max_f32_e32 v6, 0, v6
	v_max_f32_e32 v7, 0, v7
	v_pk_mul_f32 v[4:5], v[4:5], v[4:5]
	v_pk_mul_f32 v[6:7], v[6:7], v[6:7]
	v_cvt_pk_bf16_f32 v4, v4, v5
	v_cvt_pk_bf16_f32 v5, v6, v7
	ds_write_b64 v136, v[4:5] offset:25600
	v_mul_f32_e32 v0, v0, v214
	v_mul_f32_e32 v1, v1, v214
	v_mul_f32_e32 v2, v2, v214
	v_mul_f32_e32 v3, v3, v214
	v_max_f32_e32 v0, 0, v0
	v_max_f32_e32 v1, 0, v1
	v_max_f32_e32 v2, 0, v2
	v_max_f32_e32 v3, 0, v3
	v_pk_mul_f32 v[0:1], v[0:1], v[0:1]
	v_pk_mul_f32 v[2:3], v[2:3], v[2:3]
	v_cvt_pk_bf16_f32 v0, v0, v1
	v_cvt_pk_bf16_f32 v1, v2, v3
	ds_write_b64 v136, v[0:1] offset:25632
	s_waitcnt lgkmcnt(0)
	s_barrier
; DI uint2 pk4(float a, float b, float c, float d) { uint2 o; o.x = pk2(a, b); o.y = pk2(c, d); return o; }
; DI void phaseH(int wv0, PP p, unsigned char* smem) {
;     ...
;     const int tid = my_tid(wv0);
;     if (tid < 256) {
;       const float4* s = (const float4*)(SS1 + (size_t)(brow + tid) * 16);
;       const float4 a = s[0], b = s[1], c = s[2], d = s[3];
;       const float t = a.x + a.y + a.z + a.w + b.x + b.y + b.z + b.w + c.x + c.y + c.z + c.w + d.x + d.y + d.z + d.w;
;       sR[tid] = rsqrtf(t * (1.f / 1024.f) + 1e-6f);
;     }
;     ...
;     epi256(wv0, acc, brow, bcol, [&](int ai, int bj, int m, int n, int row, int col0, f32x4& v) {
;       const float ri = sR[row - brow];
;       const float a0 = fmaxf(v[0] * ri, 0.f), a1 = fmaxf(v[1] * ri, 0.f), a2 = fmaxf(v[2] * ri, 0.f), a3 = fmaxf(v[3] * ri, 0.f);
;       *(uint2*)(ACT + (size_t)row * 4096 + col0) = pk4(a0 * a0, a1 * a1, a2 * a2, a3 * a3);
;     });
;     __syncthreads();
	v_and_b32_e32 v137, 63, v142
	v_lshrrev_b32_e32 v138, 5, v137
	v_and_b32_e32 v137, 31, v137
	s_lshl_b32 s79, s89, 5
	v_add_u32_e32 v138, s79, v138
	v_mul_u32_u24_e32 v139, 528, v138
	v_lshl_add_u32 v139, v137, 4, v139
	v_add_u32_e32 v139, 32, v139
	v_add_u32_e32 v140, s46, v138
	v_lshlrev_b32_e32 v140, 13, v140
	v_lshl_add_u32 v140, v137, 4, v140
	s_lshl_b32 s79, s48, 9
	v_add_u32_e32 v140, s79, v140
	ds_read_b128 v[0:3], v139 offset:0
	ds_read_b128 v[4:7], v139 offset:1056
	ds_read_b128 v[8:11], v139 offset:2112
	ds_read_b128 v[12:15], v139 offset:3168
	ds_read_b128 v[16:19], v139 offset:4224
	ds_read_b128 v[20:23], v139 offset:5280
	ds_read_b128 v[24:27], v139 offset:6336
	ds_read_b128 v[28:31], v139 offset:7392
	ds_read_b128 v[32:35], v139 offset:8448
	ds_read_b128 v[36:39], v139 offset:9504
	ds_read_b128 v[40:43], v139 offset:10560
	ds_read_b128 v[44:47], v139 offset:11616
	ds_read_b128 v[48:51], v139 offset:12672
	ds_read_b128 v[52:55], v139 offset:13728
	ds_read_b128 v[56:59], v139 offset:14784
	ds_read_b128 v[60:63], v139 offset:15840
	v_add_u32_e32 v217, 0x4000, v140
	v_add_u32_e32 v218, 0x8000, v140
	v_add_u32_e32 v219, 0xc000, v140
	v_add_u32_e32 v220, 0x10000, v140
	v_add_u32_e32 v221, 0x14000, v140
	v_add_u32_e32 v222, 0x18000, v140
	v_add_u32_e32 v223, 0x1c000, v140
	v_add_u32_e32 v224, 0x20000, v140
	v_add_u32_e32 v225, 0x24000, v140
	v_add_u32_e32 v226, 0x28000, v140
	v_add_u32_e32 v227, 0x2c000, v140
	v_add_u32_e32 v228, 0x30000, v140
	v_add_u32_e32 v229, 0x34000, v140
	v_add_u32_e32 v230, 0x38000, v140
	v_add_u32_e32 v231, 0x3c000, v140
	s_cmpk_lt_i32 s88, 0x800
	s_cbranch_scc0 .Lmy_hn_nocomp
	s_waitcnt vmcnt(0)
	v_and_b32_e32 v184, 0xff, v142
	v_lshl_add_u32 v184, v184, 2, 32
	v_add_u32_e32 v184, 0x213e0, v184
	v_add_f32_e32 v185, v168, v169
	v_add_f32_e32 v185, v185, v170
	v_add_f32_e32 v185, v185, v171
	v_add_f32_e32 v185, v185, v172
	v_add_f32_e32 v185, v185, v173
	v_add_f32_e32 v185, v185, v174
	v_add_f32_e32 v185, v185, v175
	v_add_f32_e32 v185, v185, v176
	v_add_f32_e32 v185, v185, v177
	v_add_f32_e32 v185, v185, v178
	v_add_f32_e32 v185, v185, v179
	v_add_f32_e32 v185, v185, v180
	v_add_f32_e32 v185, v185, v181
	v_add_f32_e32 v185, v185, v182
	v_add_f32_e32 v185, v185, v183
	v_fmamk_f32 v185, v185, 0x3a800000, v143
	v_mul_f32_e32 v186, 0x4b800000, v185
	v_cmp_gt_f32_e32 vcc, s66, v185
	s_nop 1
	v_cndmask_b32_e32 v185, v185, v186, vcc
	v_rsq_f32_e32 v185, v185
	s_nop 0
	v_mul_f32_e32 v186, 0x45800000, v185
	v_cndmask_b32_e32 v185, v185, v186, vcc
.Lmy_hn_nocomp:
	s_waitcnt lgkmcnt(15)
	global_store_dwordx4 v140, v[0:3], s[10:11]
	s_waitcnt lgkmcnt(14)
	global_store_dwordx4 v217, v[4:7], s[10:11]
	s_waitcnt lgkmcnt(13)
	global_store_dwordx4 v218, v[8:11], s[10:11]
	s_waitcnt lgkmcnt(12)
	global_store_dwordx4 v219, v[12:15], s[10:11]
	s_waitcnt lgkmcnt(11)
	global_store_dwordx4 v220, v[16:19], s[10:11]
	s_waitcnt lgkmcnt(10)
	global_store_dwordx4 v221, v[20:23], s[10:11]
	s_waitcnt lgkmcnt(9)
	global_store_dwordx4 v222, v[24:27], s[10:11]
	s_waitcnt lgkmcnt(8)
	global_store_dwordx4 v223, v[28:31], s[10:11]
	s_waitcnt lgkmcnt(7)
	global_store_dwordx4 v224, v[32:35], s[10:11]
	s_waitcnt lgkmcnt(6)
	global_store_dwordx4 v225, v[36:39], s[10:11]
	s_waitcnt lgkmcnt(5)
	global_store_dwordx4 v226, v[40:43], s[10:11]
	s_waitcnt lgkmcnt(4)
	global_store_dwordx4 v227, v[44:47], s[10:11]
	s_waitcnt lgkmcnt(3)
	global_store_dwordx4 v228, v[48:51], s[10:11]
	s_waitcnt lgkmcnt(2)
	global_store_dwordx4 v229, v[52:55], s[10:11]
	s_waitcnt lgkmcnt(1)
	global_store_dwordx4 v230, v[56:59], s[10:11]
	s_waitcnt lgkmcnt(0)
	global_store_dwordx4 v231, v[60:63], s[10:11]
	s_cmpk_lt_i32 s88, 0x800
	s_cbranch_scc0 .Lmy_hn_nowr
	ds_write_b32 v184, v185
.Lmy_hn_nowr:
	s_barrier
	s_load_dword s4, s[16:17], 0x0
	s_waitcnt lgkmcnt(0)
	s_add_i32 s67, s4, s67
	s_cmpk_lt_i32 s67, 0x800
	s_cbranch_scc0 .Lmy_hn_exit
; DI void gemm256(int wv0, f32x4 (&acc)[2][2][4][2], const u16* __restrict__ A, int lda, const u16* __restrict__ Bt, int ldb,
;                 int K, unsigned char* smem) {
;   u16* shm = (u16*)smem;
;   const int tid = my_tid(wv0), lane = tid & 63;
;   const int wr = wv0 >> 2, wc = wv0 & 3, fr = lane & 15, fq = lane >> 4;
;     ...
;   int sr0, sc0, sr1, sc1;
;   stage_rc(tid * 16, sr0, sc0);
;   stage_rc(tid * 16 + 8192, sr1, sc1);
;   const u16* a0 = A + (size_t)sr0 * lda + sc0;
;   const u16* a1 = A + (size_t)sr1 * lda + sc1;
;   const u16* b0 = Bt + (size_t)sr0 * ldb + sc0;
;   const u16* b1 = Bt + (size_t)sr1 * ldb + sc1;
; DI void phaseH(int wv0, PP p, unsigned char* smem) {
;     ...
;   for (int id = blockIdx.x; id < 128 * 16; id += gridDim.x) {
;     int pm, pn;
;     tile_map_n16(id, pm, pn);
;     const int brow = pm * 256, bcol = pn * 256;
;     const int tid = my_tid(wv0);
;     if (tid < 256) {
;       const float4* s = (const float4*)(SS1 + (size_t)(brow + tid) * 16);
;       const float4 a = s[0], b = s[1], c = s[2], d = s[3];
;       const float t = a.x + a.y + a.z + a.w + b.x + b.y + b.z + b.w + c.x + c.y + c.z + c.w + d.x + d.y + d.z + d.w;
;       sR[tid] = rsqrtf(t * (1.f / 1024.f) + 1e-6f);
;     }
.LBB0_1134:
	s_ashr_i32 s4, s67, 4
	s_and_b32 s68, s4, -16
	s_lshl_b32 s4, s67, 1
	s_and_b32 s69, s4, 12
	s_or_b32 s4, s68, s69
	s_bfe_u32 s70, s67, 0x20006
	s_or_b32 s4, s4, s70
	s_lshl_b32 s46, s4, 8
	s_nop 0
	s_cmp_lg_u32 s80, 0
	s_cbranch_scc1 .LBB0_1136
	v_and_b32_e32 v0, 0xff, v142
	v_add_u32_e32 v2, s46, v0
	v_ashrrev_i32_e32 v3, 31, v2
	v_lshlrev_b64 v[2:3], 6, v[2:3]
	v_lshl_add_u64 v[14:15], s[8:9], 0, v[2:3]
	global_load_dwordx4 v[168:171], v[14:15], off
	global_load_dwordx4 v[172:175], v[14:15], off offset:16
	global_load_dwordx4 v[176:179], v[14:15], off offset:32
	global_load_dwordx4 v[180:183], v[14:15], off offset:48
.LBB0_1136:
	v_mov_b32_e32 v12, v142
	s_lshl_b32 s4, s67, 3
	v_bfe_i32 v1, v12, 27, 1
	v_lshlrev_b32_e32 v13, 4, v12
	v_lshrrev_b32_e32 v1, 22, v1
	v_add_u32_e32 v1, v13, v1
	v_and_b32_e32 v1, 0xfffffc00, v1
	v_ashrrev_i32_e32 v0, 31, v12
	v_sub_u32_e32 v1, v13, v1
	v_lshrrev_b32_e32 v0, 26, v0
	v_lshrrev_b32_e32 v2, 4, v1
	v_add_u32_e32 v0, v12, v0
	v_bitop3_b32 v2, v2, v1, 32 bitop3:0x6c
	v_ashrrev_i32_e32 v1, 31, v1
	v_ashrrev_i32_e32 v0, 6, v0
	v_lshrrev_b32_e32 v1, 26, v1
	v_lshlrev_b32_e32 v3, 3, v0
	v_add_u32_e32 v1, v2, v1
	v_and_b32_e32 v3, -16, v3
	v_ashrrev_i32_e32 v1, 6, v1
	v_add_u32_e32 v4, v1, v3
	v_mul_i32_i24_e32 v1, 64, v1
	v_lshlrev_b32_e32 v0, 5, v0
	v_sub_u32_e32 v1, v2, v1
	v_and_b32_e32 v0, 32, v0
	v_ashrrev_i16_sdwa v1, v144, sext(v1) dst_sel:DWORD dst_unused:UNUSED_PAD src0_sel:DWORD src1_sel:BYTE_0
	v_add_u32_sdwa v0, v0, sext(v1) dst_sel:DWORD dst_unused:UNUSED_PAD src0_sel:DWORD src1_sel:WORD_0
	v_add_u32_e32 v1, 0x2000, v13
	v_ashrrev_i32_e32 v2, 31, v1
	v_lshrrev_b32_e32 v2, 22, v2
	v_add_u32_e32 v2, v1, v2
	v_ashrrev_i32_e32 v2, 10, v2
	v_mul_i32_i24_e32 v3, 0x400, v2
	v_sub_u32_e32 v1, v1, v3
	v_lshrrev_b32_e32 v3, 4, v1
	v_bitop3_b32 v1, v3, v1, 32 bitop3:0x6c
	s_and_b32 s47, s4, 8
	s_bfe_u32 s4, s67, 0x30003
	v_ashrrev_i32_e32 v5, 31, v1
	s_or_b32 s48, s47, s4
	s_ashr_i32 s47, s46, 31
	v_lshrrev_b32_e32 v5, 26, v5
	s_lshl_b64 s[72:73], s[46:47], 11
	v_lshlrev_b32_e32 v3, 3, v2
	v_add_u32_e32 v5, v1, v5
	s_add_u32 s72, s0, s72
	v_and_b32_e32 v3, -16, v3
	v_ashrrev_i32_e32 v6, 6, v5
	s_addc_u32 s73, s1, s73
	s_lshl_b32 s47, s48, 19
	v_add_u32_e32 v8, v6, v3
	v_and_b32_e32 v3, 0xc0, v5
	s_add_u32 s74, s33, s47
	v_lshlrev_b32_e32 v2, 5, v2
	v_sub_u32_e32 v1, v1, v3
	s_addc_u32 s75, s50, 0
	v_and_b32_e32 v2, 32, v2
	v_ashrrev_i16_sdwa v1, v144, sext(v1) dst_sel:DWORD dst_unused:UNUSED_PAD src0_sel:DWORD src1_sel:BYTE_0
	v_ashrrev_i32_e32 v5, 31, v4
	s_add_i32 s47, 32, 0x10000
	v_add_u32_sdwa v2, v2, sext(v1) dst_sel:DWORD dst_unused:UNUSED_PAD src0_sel:DWORD src1_sel:WORD_0
	v_ashrrev_i32_e32 v1, 31, v0
	v_ashrrev_i32_e32 v9, 31, v8
	v_lshlrev_b64 v[6:7], 11, v[4:5]
	v_add_u32_e32 v148, s47, v13
	v_ashrrev_i32_e32 v3, 31, v2
	v_lshl_add_u64 v[10:11], s[74:75], 0, v[6:7]
	v_lshlrev_b64 v[4:5], 11, v[8:9]
	v_lshlrev_b64 v[16:17], 1, v[0:1]
	v_readfirstlane_b32 s47, v148
	v_add_u32_e32 v149, 0x2000, v148
	v_lshl_add_u64 v[8:9], s[74:75], 0, v[4:5]
	v_lshlrev_b64 v[18:19], 1, v[2:3]
	v_lshl_add_u64 v[10:11], v[10:11], 0, v[16:17]
	s_mov_b32 m0, s47
	v_readfirstlane_b32 s47, v149
	v_add_u32_e32 v150, 32, v13
	v_lshl_add_u64 v[14:15], s[72:73], 0, v[6:7]
	v_lshl_add_u64 v[8:9], v[8:9], 0, v[18:19]
	s_cmp_lg_u32 s80, 0
	s_cbranch_scc1 .Lmy_hn_pro_skip
	s_waitcnt vmcnt(0)
	s_waitcnt vmcnt(0) lgkmcnt(0)
	v_and_b32_e32 v184, 0xff, v142
	v_lshl_add_u32 v184, v184, 2, 32
	v_add_u32_e32 v184, 0x213e0, v184
	v_add_f32_e32 v185, v168, v169
	v_add_f32_e32 v185, v185, v170
	v_add_f32_e32 v185, v185, v171
	v_add_f32_e32 v185, v185, v172
	v_add_f32_e32 v185, v185, v173
	v_add_f32_e32 v185, v185, v174
	v_add_f32_e32 v185, v185, v175
	v_add_f32_e32 v185, v185, v176
	v_add_f32_e32 v185, v185, v177
	v_add_f32_e32 v185, v185, v178
	v_add_f32_e32 v185, v185, v179
	v_add_f32_e32 v185, v185, v180
	v_add_f32_e32 v185, v185, v181
	v_add_f32_e32 v185, v185, v182
	v_add_f32_e32 v185, v185, v183
	v_fmamk_f32 v185, v185, 0x3a800000, v143
	v_mul_f32_e32 v186, 0x4b800000, v185
	v_cmp_gt_f32_e32 vcc, s66, v185
	s_nop 1
	v_cndmask_b32_e32 v185, v185, v186, vcc
	v_rsq_f32_e32 v185, v185
	s_nop 0
	v_mul_f32_e32 v186, 0x45800000, v185
	v_cndmask_b32_e32 v185, v185, v186, vcc
	ds_write_b32 v184, v185
	s_branch .Lmy_hn_pro_join

; #define WAIT_V(n) asm volatile("s_waitcnt vmcnt(" #n ")" ::: "memory")
; #define BAR __builtin_amdgcn_s_barrier()
; DI void gemm256(int wv0, f32x4 (&acc)[2][2][4][2], const u16* __restrict__ A, int lda, const u16* __restrict__ Bt, int ldb,
;                 int K, unsigned char* smem) {
;     ...
;   WAIT_V(0);
;   __syncthreads();
;   STAGE_B(SB(0, 0), 0, 0) STAGE_A(SA(0, 0), 0, 0)
;   STAGE_B(SB(0, 1), 1, 0) STAGE_A(SA(0, 1), 1, 0)
;   if (wr == 1) BAR;
.Lmy_hn_pro_join:
	s_barrier
	global_load_lds_dwordx4 v[10:11], off
	s_mov_b32 m0, s47
	v_readfirstlane_b32 s47, v150
	v_add_u32_e32 v151, 0x2000, v150
	v_lshl_add_u64 v[132:133], v[14:15], 0, v[16:17]
	global_load_lds_dwordx4 v[8:9], off
	s_mov_b32 m0, s47
	v_readfirstlane_b32 s47, v151
	global_load_lds_dwordx4 v[132:133], off
	s_mov_b32 m0, s47
	s_add_i32 s47, 32, 0x14000
	v_lshl_add_u64 v[14:15], s[72:73], 0, v[4:5]
	v_add_u32_e32 v152, s47, v13
	v_lshl_add_u64 v[130:131], v[14:15], 0, v[18:19]
	v_readfirstlane_b32 s47, v152
	v_add_u32_e32 v153, 0x2000, v152
	global_load_lds_dwordx4 v[130:131], off
	v_lshl_add_u64 v[14:15], v[10:11], 0, s[18:19]
	s_mov_b32 m0, s47
	v_readfirstlane_b32 s47, v153
	v_add_u32_e32 v154, 0x4000, v150
	global_load_lds_dwordx4 v[14:15], off
	v_lshl_add_u64 v[14:15], v[8:9], 0, s[18:19]
	s_mov_b32 m0, s47
	v_readfirstlane_b32 s47, v154
	v_add_u32_e32 v155, 0x6000, v150
	global_load_lds_dwordx4 v[14:15], off
	v_lshl_add_u64 v[14:15], v[132:133], 0, s[18:19]
	s_mov_b32 m0, s47
	v_readfirstlane_b32 s47, v155
	global_load_lds_dwordx4 v[14:15], off
	v_lshl_add_u64 v[14:15], v[130:131], 0, s[18:19]
	s_mov_b32 m0, s47
	s_andn2_b64 vcc, exec, s[12:13]
	global_load_lds_dwordx4 v[14:15], off
	s_cbranch_vccnz .LBB0_1138
	s_barrier
